# diff tile loop: score-accumulator preset and prefetch address arithmetic moved above the tile barrier (MFMA-first segment head)
# baseline (speedup 1.0000x reference)
; #define ALAS __attribute__((address_space(3)))
; __device__ __forceinline__ int kperm(int i) { return (i & 19) | ((i & 4) << 1) | ((i & 8) >> 1); }
; template <int OFF> __device__ __forceinline__ void ldsr(bf16x8& d, unsigned a) { asm volatile("ds_read_b128 %0, %1 offset:%c2" : "=v"(d) : "v"(a), "i"(OFF) : "memory"); }
; __device__ __forceinline__ void lds_wait8(bf16x8 (&a)[8]) { asm volatile("s_waitcnt lgkmcnt(0)" : "+v"(a[0]), "+v"(a[1]), "+v"(a[2]), "+v"(a[3]), "+v"(a[4]), "+v"(a[5]), "+v"(a[6]), "+v"(a[7]) :: "memory"); }
; __device__ __forceinline__ void qk_tile(f32x16& s0, f32x16& s1, float ci, const ALAS unsigned char* Kb, const bf16x8 (&qf)[4], int r32, int hi) {
;     const unsigned p0 = (unsigned)(uintptr_t)(Kb + kperm(r32) * ROWB + hi * 16);
;     bf16x8 a[8];
;     ldsr<0>(a[0], p0); ldsr<32 * ROWB>(a[1], p0); ldsr<32>(a[2], p0); ldsr<32 * ROWB + 32>(a[3], p0);
;     ldsr<64>(a[4], p0); ldsr<32 * ROWB + 64>(a[5], p0); ldsr<96>(a[6], p0); ldsr<32 * ROWB + 96>(a[7], p0);
; #pragma unroll
;     for (int r = 0; r < 16; ++r) { s0[r] = ci; s1[r] = ci; }
;     lds_wait8(a); __builtin_amdgcn_sched_barrier(0);
; #pragma unroll
;     for (int d0 = 0; d0 < 4; ++d0) {
;         s0 = __builtin_amdgcn_mfma_f32_32x32x16_bf16(a[2 * d0], qf[d0], s0, 0, 0, 0);
;         s1 = __builtin_amdgcn_mfma_f32_32x32x16_bf16(a[2 * d0 + 1], qf[d0], s1, 0, 0, 0);
;     }
; __device__ __forceinline__ void diff_unit(int b, int hd, int qb, const bf16_t* Q, const bf16_t* K, const bf16_t* VT, bf16_t* O, const float* biasd, float lam, const float* subg, ALAS unsigned char* lds) {
;     ...
;         if (t + 1 < NT) {
; #pragma unroll
;             for (int i = 0; i < 2; ++i) { kr[i] = *(const u32x4*)(kg[i] + (size_t)(t + 1) * 64 * 1024); vr[i] = *(const u32x4*)(vg[i] + (t + 1) * 64); }
;         }
;         const int kbase = 64 * t;
;         if (kbase <= q0 + 31) {
;             const bool far = (q0 - (kbase + 63)) >= 128;
;             f32x16 s0, s1; const float ci = (far ? cb : 0.f) - mref;
;             qk_tile(s0, s1, ci, buf + map * 9216, qf, r32, hi);
;             if (!far) near_bias(s0, s1, bt, qpos, kbase, hi);
.Ldf_504b:
	s_bitcmp1_b32 s14, 0
	s_cselect_b32 s4, 0, 0x9000
	s_add_i32 s18, s4, 0
	s_cmpk_gt_i32 s12, 0x7f
	s_cselect_b64 vcc, -1, 0
	s_add_i32 s4, s17, 64
	s_lshl_b64 s[36:37], s[4:5], 1
	v_cndmask_b32_e32 v64, 0, v137, vcc
	v_sub_f32_e32 v64, v64, v163
	v_mov_b32_e32 v65, v64
	v_mov_b64_e32 v[66:67], v[64:65]
	v_mov_b64_e32 v[68:69], v[64:65]
	v_mov_b64_e32 v[70:71], v[64:65]
	v_mov_b64_e32 v[72:73], v[64:65]
	v_mov_b64_e32 v[74:75], v[64:65]
	v_mov_b64_e32 v[76:77], v[64:65]
	v_mov_b64_e32 v[78:79], v[64:65]
	v_lshl_add_u64 v[148:149], v[156:157], 0, s[36:37]
	v_lshl_add_u64 v[150:151], v[140:141], 0, s[36:37]
	s_waitcnt vmcnt(3)
	ds_write_b128 v138, v[112:115] offset:0
	s_waitcnt vmcnt(1)
	ds_write_b128 v158, v[116:119] offset:18432
	ds_write_b128 v142, v[120:123] offset:0
	s_cmp_ge_i32 s14, s16
	s_waitcnt vmcnt(0)
	ds_write_b128 v160, v[124:127] offset:18432
	s_waitcnt lgkmcnt(0)
	s_barrier
	ds_read_b128 v[172:175], v146 offset:0
	ds_read_b128 v[176:179], v146 offset:4608
	ds_read_b128 v[180:183], v146 offset:32
	ds_read_b128 v[184:187], v146 offset:4640
	ds_read_b128 v[188:191], v146 offset:64
	ds_read_b128 v[192:195], v146 offset:4672
	ds_read_b128 v[196:199], v146 offset:96
	ds_read_b128 v[216:219], v146 offset:4704
	s_cbranch_scc1 .Ldf_506b
	global_load_dwordx4 v[112:115], v[164:165], off
	global_load_dwordx4 v[120:123], v[166:167], off
	global_load_dwordx4 v[116:119], v[150:151], off
	global_load_dwordx4 v[124:127], v[148:149], off
.Ldf_506b:
	s_cmp_gt_i32 s17, s15
	s_cbranch_scc1 .Ldf_503b
	s_waitcnt lgkmcnt(6)
	s_nop 1
	v_mfma_f32_32x32x16_bf16 v[80:95], v[172:175], v[108:111], v[64:79]
	s_and_b64 vcc, exec, vcc
	v_mfma_f32_32x32x16_bf16 v[64:79], v[176:179], v[108:111], v[64:79]
	s_waitcnt lgkmcnt(4)
	v_mfma_f32_32x32x16_bf16 v[80:95], v[180:183], v[104:107], v[80:95]
	v_mfma_f32_32x32x16_bf16 v[64:79], v[184:187], v[104:107], v[64:79]
	s_waitcnt lgkmcnt(2)
	v_mfma_f32_32x32x16_bf16 v[80:95], v[188:191], v[100:103], v[80:95]
	v_mfma_f32_32x32x16_bf16 v[64:79], v[192:195], v[100:103], v[64:79]
	s_waitcnt lgkmcnt(0)
	v_mfma_f32_32x32x16_bf16 v[80:95], v[196:199], v[96:99], v[80:95]
	v_mfma_f32_32x32x16_bf16 v[64:79], v[216:219], v[96:99], v[64:79]
	s_cbranch_vccnz .Ldf_509b
	v_add_u32_e32 v161, s12, v159
	v_lshlrev_b32_e32 v161, 2, v161
	s_lshl_b32 s4, s9, 11
	s_add_i32 s4, s4, 0x12c20
	v_add_u32_e32 v161, s4, v161
	ds_read_b32 v172, v161 offset:92
	ds_read_b32 v173, v161 offset:88
	ds_read_b32 v174, v161 offset:84
	ds_read_b32 v175, v161 offset:80
	ds_read_b32 v176, v161 offset:76
	ds_read_b32 v177, v161 offset:72
	ds_read_b32 v178, v161 offset:68
	ds_read_b32 v179, v161 offset:64
	ds_read_b32 v180, v161 offset:28
	ds_read_b32 v181, v161 offset:24
	ds_read_b32 v182, v161 offset:20
	ds_read_b32 v183, v161 offset:16
	ds_read_b32 v184, v161 offset:12
	ds_read_b32 v185, v161 offset:8
	ds_read_b32 v186, v161 offset:4
	ds_read_b32 v187, v161 offset:0
	ds_read_b32 v188, v161 offset:220
	ds_read_b32 v189, v161 offset:216
	ds_read_b32 v190, v161 offset:212
	ds_read_b32 v191, v161 offset:208
	ds_read_b32 v192, v161 offset:204
	ds_read_b32 v193, v161 offset:200
	ds_read_b32 v194, v161 offset:196
	ds_read_b32 v195, v161 offset:192
	ds_read_b32 v196, v161 offset:156
	ds_read_b32 v197, v161 offset:152
	ds_read_b32 v198, v161 offset:148
	ds_read_b32 v199, v161 offset:144
	ds_read_b32 v216, v161 offset:140
	ds_read_b32 v217, v161 offset:136
	ds_read_b32 v218, v161 offset:132
	ds_read_b32 v219, v161 offset:128
	s_waitcnt lgkmcnt(0)
	v_add_f32_e32 v64, v64, v172
	v_add_f32_e32 v65, v65, v173
	v_add_f32_e32 v66, v66, v174
	v_add_f32_e32 v67, v67, v175
	v_add_f32_e32 v68, v68, v176
	v_add_f32_e32 v69, v69, v177
	v_add_f32_e32 v70, v70, v178
	v_add_f32_e32 v71, v71, v179
	v_add_f32_e32 v72, v72, v180
	v_add_f32_e32 v73, v73, v181
	v_add_f32_e32 v74, v74, v182
	v_add_f32_e32 v75, v75, v183
	v_add_f32_e32 v76, v76, v184
	v_add_f32_e32 v77, v77, v185
	v_add_f32_e32 v78, v78, v186
	v_add_f32_e32 v79, v79, v187
	v_add_f32_e32 v80, v80, v188
	v_add_f32_e32 v81, v81, v189
	v_add_f32_e32 v82, v82, v190
	v_add_f32_e32 v83, v83, v191
	v_add_f32_e32 v84, v84, v192
	v_add_f32_e32 v85, v85, v193
	v_add_f32_e32 v86, v86, v194
	v_add_f32_e32 v87, v87, v195
	v_add_f32_e32 v88, v88, v196
	v_add_f32_e32 v89, v89, v197
	v_add_f32_e32 v90, v90, v198
	v_add_f32_e32 v91, v91, v199
	v_add_f32_e32 v92, v92, v216
	v_add_f32_e32 v93, v93, v217
	v_add_f32_e32 v94, v94, v218
	v_add_f32_e32 v95, v95, v219

; #define ALAS __attribute__((address_space(3)))
; __device__ __forceinline__ void diff_unit(int b, int hd, int qb, const bf16_t* Q, const bf16_t* K, const bf16_t* VT, bf16_t* O, const float* biasd, float lam, const float* subg, ALAS unsigned char* lds) {
;     ...
;         ALAS unsigned char* buf = lds + (t & 1) * 36864;
; #pragma unroll
;         for (int i = 0; i < 2; ++i) { *(ALAS u32x4*)(buf + kl[i]) = kr[i]; *(ALAS u32x4*)(buf + vl[i]) = vr[i]; }
;         __syncthreads();
;         if (t + 1 < NT) {
; #pragma unroll
;             for (int i = 0; i < 2; ++i) { kr[i] = *(const u32x4*)(kg[i] + (size_t)(t + 1) * 64 * 1024); vr[i] = *(const u32x4*)(vg[i] + (t + 1) * 64); }
;         }
;         const int kbase = 64 * t;
;         if (kbase <= q0 + 31) {
;             const bool far = (q0 - (kbase + 63)) >= 128;
;             f32x16 s0, s1; const float ci = (far ? cb : 0.f) - mref;
.LBB0_504:
	s_bitcmp1_b32 s14, 0
	s_cselect_b32 s4, 0, 0x9000
	s_add_i32 s18, s4, 0
	s_cmpk_gt_i32 s12, 0x7f
	s_cselect_b64 vcc, -1, 0
	s_add_i32 s4, s17, 64
	s_lshl_b64 s[36:37], s[4:5], 1
	v_cndmask_b32_e32 v64, 0, v137, vcc
	v_sub_f32_e32 v64, v64, v163
	v_mov_b32_e32 v65, v64
	v_mov_b64_e32 v[66:67], v[64:65]
	v_mov_b64_e32 v[68:69], v[64:65]
	v_mov_b64_e32 v[70:71], v[64:65]
	v_mov_b64_e32 v[72:73], v[64:65]
	v_mov_b64_e32 v[74:75], v[64:65]
	v_mov_b64_e32 v[76:77], v[64:65]
	v_mov_b64_e32 v[78:79], v[64:65]
	v_lshl_add_u64 v[148:149], v[156:157], 0, s[36:37]
	v_lshl_add_u64 v[150:151], v[140:141], 0, s[36:37]
	s_waitcnt vmcnt(3)
	ds_write_b128 v138, v[112:115] offset:36864
	s_waitcnt vmcnt(1)
	ds_write_b128 v158, v[116:119] offset:55296
	ds_write_b128 v142, v[120:123] offset:36864
	s_cmp_ge_i32 s14, s16
	s_waitcnt vmcnt(0)
	ds_write_b128 v160, v[124:127] offset:55296
	s_waitcnt lgkmcnt(0)
	s_barrier
	ds_read_b128 v[172:175], v146 offset:36864
	ds_read_b128 v[176:179], v146 offset:41472
	ds_read_b128 v[180:183], v146 offset:36896
	ds_read_b128 v[184:187], v146 offset:41504
	ds_read_b128 v[188:191], v146 offset:36928
	ds_read_b128 v[192:195], v146 offset:41536
	ds_read_b128 v[196:199], v146 offset:36960
	ds_read_b128 v[216:219], v146 offset:41568
	s_cbranch_scc1 .LBB0_506
	global_load_dwordx4 v[112:115], v[164:165], off
	global_load_dwordx4 v[120:123], v[166:167], off
	global_load_dwordx4 v[116:119], v[150:151], off
	global_load_dwordx4 v[124:127], v[148:149], off

; #define SEAM(k) do { if (IN(k) && IN((k) + 1)) { xcd_barrier(bar); } } while (0)
; __device__ __forceinline__ void xcd_barrier(const XcdBarrier& b) {
;     asm volatile("s_waitcnt vmcnt(0)" ::: "memory");
;     __syncthreads();
;     if (threadIdx.x == 0) {
;         unsigned* bar = b.bar;
;         __builtin_amdgcn_s_waitcnt(0);
;         unsigned nloc = b.st[0], nx = b.st[1];
;         if (nloc == 0u) { xcd_barrier_complete(bar, b.x, nloc, nx); b.st[0] = nloc; b.st[1] = nx; }
; __global__ void __launch_bounds__(512, 2) fwd_kernel(Params p) {
;     ...
;         SEAM(pb + 3);
;         if (IN(pb + 4)) { pg8::EpiResid<false> E{nullptr, XA, ss + (size_t)(3 * l + 2) * MTOK * 16, 1.0f}; run_gemm(lds, Ob, Wo, MTOK, 1024, 1024, E); }
.LBB0_546:
	v_mov_b64_e32 v[146:147], 0xb00
	v_mov_b64_e32 v[148:149], 0xaff
	v_mov_b64_e32 v[150:151], 0x200
	s_mul_i32 s0, s52, 7
	s_add_i32 s4, s0, 5
	s_cmp_lt_i32 s4, s90
	s_cselect_b64 s[0:1], -1, 0
	s_and_b64 s[6:7], s[28:29], s[0:1]
	s_andn2_b64 vcc, exec, s[6:7]
	s_cbranch_vccnz .LBB0_600
	s_waitcnt vmcnt(0)
	s_waitcnt lgkmcnt(0)
	s_barrier
	s_mov_b64 s[6:7], exec
	v_readlane_b32 s8, v254, 3
	v_readlane_b32 s9, v254, 4
	s_and_b64 s[8:9], s[6:7], s[8:9]
	s_mov_b64 exec, s[8:9]
	s_cbranch_execz .LBB0_599
	v_readlane_b32 s8, v255, 24
	s_waitcnt vmcnt(0) expcnt(0) lgkmcnt(0)
	s_nop 0
	v_mov_b32_e32 v0, s8
	ds_read_b32 v2, v0
	v_readlane_b32 s8, v255, 25
	s_waitcnt lgkmcnt(0)
	v_cmp_ne_u32_e32 vcc, 0, v2
	v_mov_b32_e32 v0, s8
	ds_read_b32 v0, v0
	s_cbranch_vccnz .LBB0_563
	s_mov_b32 s14, 1
	s_branch .LBB0_551
